# attention epilogue: the 16 row-sum LDS reads batched up front (one wait) instead of one exposed LDS round trip per row
# baseline (speedup 1.0000x reference)
; DI unsigned short f2bf(float f) { return (unsigned short)(cvtpk(f, f) & 0xffffu); }
; DI int crow(int r, int hi) { return (r & 3) + 8 * (r >> 2) + 4 * hi; }
; DI void attn_item(const bf16_t* __restrict__ Qw_, const bf16_t* __restrict__ Kh, const bf16_t* __restrict__ Vh, const bf16_t* Gw, bf16_t* Ow,
;                   int NT, int kt0, int qw, float sinkv, char* lds) {
;     ...
;     if (hi == 0) li_l[r32] = l_reg; asm volatile("s_waitcnt lgkmcnt(0)" ::: "memory");
;     bf16_t* OT = (bf16_t*)(lds + 67584 + wid * 8704);
; #pragma unroll
;     for (int r = 0; r < 16; ++r) { const int orow = crow(r, hi); const float rl = __builtin_amdgcn_rcpf(li_l[orow]);
; #pragma unroll
;         for (int d0 = 0; d0 < 4; ++d0) OT[orow * 136 + d0 * 32 + r32] = f2bf(o[d0][r] * rl); }
.LBB0_237:
	s_or_b64 exec, exec, s[4:5]
	s_waitcnt lgkmcnt(0)
	v_lshl_add_u32 v0, v193, 2, s54
	s_lshl_b64 s[4:5], s[14:15], 12
	ds_read_b32 v70, v0
	ds_read_b32 v71, v0 offset:4
	ds_read_b32 v72, v0 offset:8
	ds_read_b32 v73, v0 offset:12
	ds_read_b32 v74, v0 offset:32
	ds_read_b32 v75, v0 offset:36
	ds_read_b32 v76, v0 offset:40
	ds_read_b32 v77, v0 offset:44
	ds_read_b32 v78, v0 offset:64
	ds_read_b32 v79, v0 offset:68
	ds_read_b32 v80, v0 offset:72
	ds_read_b32 v81, v0 offset:76
	ds_read_b32 v82, v0 offset:96
	ds_read_b32 v83, v0 offset:100
	ds_read_b32 v84, v0 offset:104
	ds_read_b32 v85, v0 offset:108
	s_add_u32 s4, s23, s4
	s_addc_u32 s5, s30, s5
	s_lshl_b32 s14, s53, 1
	s_add_u32 s4, s4, s14
	s_addc_u32 s5, s5, 0
	s_lshr_b32 s14, s52, 6
	s_mulk_i32 s14, 0x2200
	s_waitcnt lgkmcnt(0)
	v_rcp_f32_e32 v67, v70
	s_add_i32 s14, s14, 0
	s_add_i32 s14, s14, 0x10800
	v_lshl_add_u32 v68, v188, 1, s14
	v_add_u32_e32 v69, v68, v196
	v_mul_f32_e32 v50, v50, v67
	v_mul_f32_e32 v34, v34, v67
	v_mul_f32_e32 v18, v18, v67
	v_cvt_pk_bf16_f32 v50, v50, v50
	ds_write_b16 v69, v50
	v_cvt_pk_bf16_f32 v34, v34, v34
	ds_write_b16 v69, v34 offset:64
	v_cvt_pk_bf16_f32 v18, v18, v18
	v_mul_f32_e32 v2, v2, v67
	ds_write_b16 v69, v18 offset:128
	v_cvt_pk_bf16_f32 v2, v2, v2
	ds_write_b16 v69, v2 offset:192
	v_add_u32_e32 v2, v68, v197
	v_rcp_f32_e32 v18, v71
	s_nop 0
	v_mul_f32_e32 v34, v51, v18
	v_cvt_pk_bf16_f32 v34, v34, v34
	ds_write_b16 v2, v34
	v_mul_f32_e32 v34, v35, v18
	v_mul_f32_e32 v19, v19, v18
	v_mul_f32_e32 v3, v3, v18
	v_cvt_pk_bf16_f32 v34, v34, v34
	ds_write_b16 v2, v34 offset:64
	v_cvt_pk_bf16_f32 v19, v19, v19
	ds_write_b16 v2, v19 offset:128
	v_cvt_pk_bf16_f32 v3, v3, v3
	ds_write_b16 v2, v3 offset:192
	v_rcp_f32_e32 v18, v72
	s_nop 0
	v_mul_f32_e32 v3, v52, v18
	v_cvt_pk_bf16_f32 v3, v3, v3
	ds_write_b16 v2, v3 offset:272
	v_mul_f32_e32 v3, v36, v18
	v_cvt_pk_bf16_f32 v3, v3, v3
	ds_write_b16 v2, v3 offset:336
	v_mul_f32_e32 v3, v20, v18
	v_cvt_pk_bf16_f32 v3, v3, v3
	ds_write_b16 v2, v3 offset:400
	v_mul_f32_e32 v3, v4, v18
	v_cvt_pk_bf16_f32 v3, v3, v3
	ds_write_b16 v2, v3 offset:464
	v_rcp_f32_e32 v4, v73
	s_nop 0
	v_mul_f32_e32 v3, v53, v4
	v_cvt_pk_bf16_f32 v3, v3, v3
	ds_write_b16 v2, v3 offset:544
	v_mul_f32_e32 v3, v37, v4
	v_cvt_pk_bf16_f32 v3, v3, v3
	ds_write_b16 v2, v3 offset:608
	v_mul_f32_e32 v3, v21, v4
	v_cvt_pk_bf16_f32 v3, v3, v3
	ds_write_b16 v2, v3 offset:672
	v_mul_f32_e32 v3, v5, v4
	v_cvt_pk_bf16_f32 v3, v3, v3
	ds_write_b16 v2, v3 offset:736
	v_rcp_f32_e32 v4, v74
	s_nop 0
	v_mul_f32_e32 v3, v54, v4
	v_cvt_pk_bf16_f32 v3, v3, v3
	ds_write_b16 v2, v3 offset:1904
	v_mul_f32_e32 v3, v38, v4
	v_cvt_pk_bf16_f32 v3, v3, v3
	ds_write_b16 v2, v3 offset:1968
	v_mul_f32_e32 v3, v22, v4
	v_cvt_pk_bf16_f32 v3, v3, v3
	ds_write_b16 v2, v3 offset:2032
	v_mul_f32_e32 v3, v6, v4
	v_cvt_pk_bf16_f32 v3, v3, v3
	ds_write_b16 v2, v3 offset:2096
	v_rcp_f32_e32 v4, v75
	s_nop 0
	v_mul_f32_e32 v3, v55, v4
	v_cvt_pk_bf16_f32 v3, v3, v3
	ds_write_b16 v2, v3 offset:2176
	v_mul_f32_e32 v3, v39, v4
	v_cvt_pk_bf16_f32 v3, v3, v3
	ds_write_b16 v2, v3 offset:2240
	v_mul_f32_e32 v3, v23, v4
	v_cvt_pk_bf16_f32 v3, v3, v3
	ds_write_b16 v2, v3 offset:2304
	v_mul_f32_e32 v3, v7, v4
	v_cvt_pk_bf16_f32 v3, v3, v3
	ds_write_b16 v2, v3 offset:2368
	v_add_u32_e32 v3, v68, v198
	v_rcp_f32_e32 v4, v76
	s_nop 0
	v_mul_f32_e32 v5, v56, v4
	v_cvt_pk_bf16_f32 v5, v5, v5
	ds_write_b16 v2, v5 offset:2448
	v_mul_f32_e32 v2, v40, v4
	v_cvt_pk_bf16_f32 v2, v2, v2
	ds_write_b16 v3, v2 offset:64
	v_mul_f32_e32 v2, v24, v4
	v_cvt_pk_bf16_f32 v2, v2, v2
	ds_write_b16 v3, v2 offset:128
	v_mul_f32_e32 v2, v8, v4
	v_cvt_pk_bf16_f32 v2, v2, v2
	ds_write_b16 v3, v2 offset:192
	v_rcp_f32_e32 v4, v77
	s_nop 0
	v_mul_f32_e32 v2, v57, v4
	v_cvt_pk_bf16_f32 v2, v2, v2
	ds_write_b16 v3, v2 offset:272
	v_mul_f32_e32 v2, v41, v4
	v_cvt_pk_bf16_f32 v2, v2, v2
	ds_write_b16 v3, v2 offset:336
	v_mul_f32_e32 v2, v25, v4
	v_cvt_pk_bf16_f32 v2, v2, v2
	ds_write_b16 v3, v2 offset:400
	v_mul_f32_e32 v2, v9, v4
	v_cvt_pk_bf16_f32 v2, v2, v2
	ds_write_b16 v3, v2 offset:464
	v_rcp_f32_e32 v4, v78
	s_nop 0
	v_mul_f32_e32 v2, v58, v4
	v_cvt_pk_bf16_f32 v2, v2, v2
	ds_write_b16 v3, v2 offset:1632
	v_mul_f32_e32 v2, v42, v4
	v_cvt_pk_bf16_f32 v2, v2, v2
	ds_write_b16 v3, v2 offset:1696
	v_mul_f32_e32 v2, v26, v4
	v_cvt_pk_bf16_f32 v2, v2, v2
	ds_write_b16 v3, v2 offset:1760
	v_mul_f32_e32 v2, v10, v4
	v_cvt_pk_bf16_f32 v2, v2, v2
	ds_write_b16 v3, v2 offset:1824
	v_rcp_f32_e32 v4, v79
	s_nop 0
	v_mul_f32_e32 v2, v59, v4
	v_cvt_pk_bf16_f32 v2, v2, v2
	ds_write_b16 v3, v2 offset:1904
	v_mul_f32_e32 v2, v43, v4
	v_cvt_pk_bf16_f32 v2, v2, v2
	ds_write_b16 v3, v2 offset:1968
	v_mul_f32_e32 v2, v27, v4
	v_cvt_pk_bf16_f32 v2, v2, v2
	ds_write_b16 v3, v2 offset:2032
	v_mul_f32_e32 v2, v11, v4
	v_cvt_pk_bf16_f32 v2, v2, v2
	ds_write_b16 v3, v2 offset:2096
	v_rcp_f32_e32 v4, v80
	s_nop 0
	v_mul_f32_e32 v2, v60, v4
	v_cvt_pk_bf16_f32 v2, v2, v2
	ds_write_b16 v3, v2 offset:2176
	v_mul_f32_e32 v2, v44, v4
	v_cvt_pk_bf16_f32 v2, v2, v2
	ds_write_b16 v3, v2 offset:2240
	v_mul_f32_e32 v2, v28, v4
	v_cvt_pk_bf16_f32 v2, v2, v2
	ds_write_b16 v3, v2 offset:2304
	v_mul_f32_e32 v2, v12, v4
	v_cvt_pk_bf16_f32 v2, v2, v2
	ds_write_b16 v3, v2 offset:2368
	v_rcp_f32_e32 v4, v81
	s_nop 0
	v_mul_f32_e32 v2, v61, v4
	v_cvt_pk_bf16_f32 v2, v2, v2
	ds_write_b16 v3, v2 offset:2448
	v_mul_f32_e32 v2, v45, v4
	v_cvt_pk_bf16_f32 v2, v2, v2
	ds_write_b16 v3, v2 offset:2512
	v_mul_f32_e32 v2, v29, v4
	v_cvt_pk_bf16_f32 v2, v2, v2
	ds_write_b16 v3, v2 offset:2576
	v_mul_f32_e32 v2, v13, v4
	v_cvt_pk_bf16_f32 v2, v2, v2
; DI unsigned cvtpk(float lo, float hi) { unsigned r; asm volatile("v_cvt_pk_bf16_f32 %0, %1, %2" : "=v"(r) : "v"(lo), "v"(hi)); return r; }
; DI float bflo(unsigned w) { return __uint_as_float(w << 16); }
; DI float bfhi(unsigned w) { return __uint_as_float(w & 0xffff0000u); }
; DI unsigned short f2bf(float f) { return (unsigned short)(cvtpk(f, f) & 0xffffu); }
; DI float sigm(float x) { return rcpf_(1.f + ex2(-x * LOG2E)); }
; DI int crow(int r, int hi) { return (r & 3) + 8 * (r >> 2) + 4 * hi; }
; DI void attn_item(const bf16_t* __restrict__ Qw_, const bf16_t* __restrict__ Kh, const bf16_t* __restrict__ Vh, const bf16_t* Gw, bf16_t* Ow,
;                   int NT, int kt0, int qw, float sinkv, char* lds) {
;     ...
;     if (hi == 0) li_l[r32] = l_reg; asm volatile("s_waitcnt lgkmcnt(0)" ::: "memory");
;     bf16_t* OT = (bf16_t*)(lds + 67584 + wid * 8704);
; #pragma unroll
;     for (int r = 0; r < 16; ++r) { const int orow = crow(r, hi); const float rl = __builtin_amdgcn_rcpf(li_l[orow]);
; #pragma unroll
;         for (int d0 = 0; d0 < 4; ++d0) OT[orow * 136 + d0 * 32 + r32] = f2bf(o[d0][r] * rl); }
;     __builtin_amdgcn_sched_barrier(0);
;     u32x4 gv[8];
; #pragma unroll
;     for (int k = 0; k < 8; ++k) gv[k] = __builtin_nontemporal_load((const u32x4*)(Gw + (size_t)(er + 4 * k) * 2048 + ec * 8));
;     asm volatile("s_waitcnt lgkmcnt(0)" ::: "memory");
; #pragma unroll
;     for (int k = 0; k < 8; ++k) {
;         const u32x4 ov = *(const u32x4*)(OT + (er + 4 * k) * 136 + ec * 8); u32x4 w;
; #pragma unroll
;         for (int i = 0; i < 4; ++i) { const float g0 = bflo(gv[k][i]), g1 = bfhi(gv[k][i]); w[i] = cvtpk(bflo(ov[i]) * g0 * sigm(g0), bfhi(ov[i]) * g1 * sigm(g1)); }
;         __builtin_nontemporal_store(w, (u32x4*)(Ow + (size_t)(er + 4 * k) * 2048 + ec * 8));
;     }
	ds_write_b16 v3, v2 offset:2640
	v_rcp_f32_e32 v4, v82
	s_nop 0
	v_mul_f32_e32 v2, v62, v4
	v_cvt_pk_bf16_f32 v2, v2, v2
	ds_write_b16 v3, v2 offset:3808
	v_mul_f32_e32 v2, v46, v4
	v_cvt_pk_bf16_f32 v2, v2, v2
	ds_write_b16 v3, v2 offset:3872
	v_mul_f32_e32 v2, v30, v4
	v_cvt_pk_bf16_f32 v2, v2, v2
	ds_write_b16 v3, v2 offset:3936
	v_mul_f32_e32 v2, v14, v4
	v_cvt_pk_bf16_f32 v2, v2, v2
	ds_write_b16 v3, v2 offset:4000
	v_rcp_f32_e32 v4, v83
	s_nop 0
	v_mul_f32_e32 v2, v63, v4
	v_cvt_pk_bf16_f32 v2, v2, v2
	ds_write_b16 v3, v2 offset:4080
	v_mul_f32_e32 v2, v47, v4
	v_cvt_pk_bf16_f32 v2, v2, v2
	ds_write_b16 v3, v2 offset:4144
	v_mul_f32_e32 v2, v31, v4
	v_cvt_pk_bf16_f32 v2, v2, v2
	ds_write_b16 v3, v2 offset:4208
	v_mul_f32_e32 v2, v15, v4
	v_cvt_pk_bf16_f32 v2, v2, v2
	ds_write_b16 v3, v2 offset:4272
	v_rcp_f32_e32 v4, v84
	s_nop 0
	v_mul_f32_e32 v2, v64, v4
	v_cvt_pk_bf16_f32 v2, v2, v2
	ds_write_b16 v3, v2 offset:4352
	v_mul_f32_e32 v2, v48, v4
	v_cvt_pk_bf16_f32 v2, v2, v2
	ds_write_b16 v3, v2 offset:4416
	v_mul_f32_e32 v2, v32, v4
	v_cvt_pk_bf16_f32 v2, v2, v2
	ds_write_b16 v3, v2 offset:4480
	v_mul_f32_e32 v2, v16, v4
	v_cvt_pk_bf16_f32 v4, v2, v2
	ds_write_b16 v3, v4 offset:4544
	v_ashrrev_i32_e32 v2, 4, v66
	v_rcp_f32_e32 v0, v85
	s_nop 0
	v_mul_f32_e32 v4, v65, v0
	v_cvt_pk_bf16_f32 v4, v4, v4
	ds_write_b16 v3, v4 offset:4624
	v_mul_f32_e32 v4, v49, v0
	v_cvt_pk_bf16_f32 v4, v4, v4
	ds_write_b16 v3, v4 offset:4688
	v_mul_f32_e32 v4, v33, v0
	v_mul_f32_e32 v0, v17, v0
	v_cvt_pk_bf16_f32 v4, v4, v4
	ds_write_b16 v3, v4 offset:4752
	v_cvt_pk_bf16_f32 v0, v0, v0
	ds_write_b16 v3, v0 offset:4816
	v_lshlrev_b32_e32 v0, 4, v66
	v_and_b32_e32 v0, 0xf0, v0
	v_ashrrev_i32_e32 v3, 31, v2
	v_lshl_add_u64 v[4:5], s[4:5], 0, v[0:1]
	v_lshlrev_b64 v[6:7], 12, v[2:3]
	v_lshl_add_u64 v[50:51], v[4:5], 0, v[6:7]
	global_load_dwordx4 v[38:41], v[50:51], off nt
	v_add_co_u32_e32 v52, vcc, s38, v50
	v_mul_lo_u32 v2, v2, s39
	s_nop 0
	v_addc_co_u32_e32 v53, vcc, 0, v51, vcc
	v_add_co_u32_e32 v36, vcc, s47, v50
	v_add3_u32 v0, s14, v0, v2
	s_nop 0
	v_addc_co_u32_e32 v37, vcc, 0, v51, vcc
	v_add_co_u32_e32 v34, vcc, s48, v50
	s_add_i32 s51, s51, s24
	s_nop 0
	v_addc_co_u32_e32 v35, vcc, 0, v51, vcc
	v_add_co_u32_e32 v32, vcc, s42, v50
	s_cmpk_lt_i32 s51, 0x400
	s_nop 0
	v_addc_co_u32_e32 v33, vcc, 0, v51, vcc
	v_add_co_u32_e32 v30, vcc, s49, v50
	s_waitcnt vmcnt(0)
	v_lshlrev_b32_e32 v57, 16, v38
	v_addc_co_u32_e32 v31, vcc, 0, v51, vcc
	v_add_co_u32_e32 v28, vcc, s36, v50
	v_and_b32_e32 v38, 0xffff0000, v38
	s_nop 0
	v_addc_co_u32_e32 v29, vcc, 0, v51, vcc
	v_add_co_u32_e32 v26, vcc, s50, v50
	v_lshlrev_b32_e32 v58, 16, v39
	s_nop 0
	v_addc_co_u32_e32 v27, vcc, 0, v51, vcc
	global_load_dwordx4 v[42:45], v[52:53], off nt
	global_load_dwordx4 v[22:25], v[36:37], off nt
	global_load_dwordx4 v[18:21], v[34:35], off nt
	global_load_dwordx4 v[14:17], v[32:33], off nt
	global_load_dwordx4 v[10:13], v[30:31], off nt
	global_load_dwordx4 v[6:9], v[28:29], off nt
	global_load_dwordx4 v[2:5], v[26:27], off nt
	s_waitcnt lgkmcnt(0)
	ds_read_b128 v[46:49], v0
	v_and_b32_e32 v39, 0xffff0000, v39
	v_lshlrev_b32_e32 v59, 16, v40
	v_and_b32_e32 v40, 0xffff0000, v40
	s_waitcnt lgkmcnt(0)
	v_lshlrev_b32_e32 v54, 16, v46
	v_and_b32_e32 v46, 0xffff0000, v46
	v_lshlrev_b32_e32 v55, 16, v47
	v_and_b32_e32 v47, 0xffff0000, v47
	v_mul_f32_e32 v46, v46, v38
	v_mul_f32_e32 v38, 0xbfb8aa3b, v38
	v_mul_f32_e32 v55, v55, v58
	v_mul_f32_e32 v58, 0xbfb8aa3b, v58
	v_mul_f32_e32 v47, v47, v39
	v_mul_f32_e32 v39, 0xbfb8aa3b, v39
	v_lshlrev_b32_e32 v56, 16, v48
	v_and_b32_e32 v48, 0xffff0000, v48
	v_mul_f32_e32 v54, v54, v57
	v_mul_f32_e32 v57, 0xbfb8aa3b, v57
	v_exp_f32_e32 v38, v38
	v_exp_f32_e32 v58, v58
	v_exp_f32_e32 v39, v39
	v_mul_f32_e32 v48, v48, v40
	v_mul_f32_e32 v40, 0xbfb8aa3b, v40
	v_exp_f32_e32 v57, v57
	v_exp_f32_e32 v40, v40
	v_add_f32_e32 v38, 1.0, v38
	v_add_f32_e32 v58, 1.0, v58
	v_add_f32_e32 v39, 1.0, v39
	v_add_f32_e32 v57, 1.0, v57
	v_rcp_f32_e32 v38, v38
	v_rcp_f32_e32 v58, v58
	v_rcp_f32_e32 v39, v39
	v_mul_f32_e32 v56, v56, v59
	v_mul_f32_e32 v59, 0xbfb8aa3b, v59
	v_add_f32_e32 v40, 1.0, v40
	v_rcp_f32_e32 v57, v57
	v_exp_f32_e32 v59, v59
	v_rcp_f32_e32 v40, v40
	v_mul_f32_e32 v38, v38, v46
	v_mul_f32_e32 v46, v58, v55
	v_mul_f32_e32 v39, v39, v47
	v_mul_f32_e32 v54, v57, v54
	v_cvt_pk_bf16_f32 v38, v54, v38
	v_cvt_pk_bf16_f32 v39, v46, v39
	v_lshlrev_b32_e32 v46, 16, v41
	v_add_f32_e32 v59, 1.0, v59
	v_mul_f32_e32 v40, v40, v48
	v_mul_f32_e32 v48, 0xbfb8aa3b, v46
	v_rcp_f32_e32 v59, v59
	v_exp_f32_e32 v48, v48
	v_and_b32_e32 v41, 0xffff0000, v41
	v_mul_f32_e32 v54, 0xbfb8aa3b, v41
	v_exp_f32_e32 v54, v54
	v_mul_f32_e32 v47, v59, v56
	v_add_f32_e32 v48, 1.0, v48
	v_cvt_pk_bf16_f32 v40, v47, v40
	v_lshlrev_b32_e32 v47, 16, v49
	v_rcp_f32_e32 v48, v48
	v_mul_f32_e32 v46, v47, v46
	v_add_f32_e32 v47, 1.0, v54
	v_rcp_f32_e32 v47, v47
	v_mul_f32_e32 v46, v48, v46
	v_and_b32_e32 v48, 0xffff0000, v49
	v_mul_f32_e32 v41, v48, v41
	v_mul_f32_e32 v41, v47, v41
	v_cvt_pk_bf16_f32 v41, v46, v41
	global_store_dwordx4 v[50:51], v[38:41], off nt
	ds_read_b128 v[46:49], v0 offset:1088
	s_waitcnt vmcnt(7)
	v_lshlrev_b32_e32 v38, 16, v42
	v_mul_f32_e32 v40, 0xbfb8aa3b, v38
	v_exp_f32_e32 v40, v40
	v_and_b32_e32 v41, 0xffff0000, v42
	v_mul_f32_e32 v42, 0xbfb8aa3b, v41
	v_exp_f32_e32 v42, v42
	v_add_f32_e32 v40, 1.0, v40
	s_waitcnt lgkmcnt(0)
; DI unsigned cvtpk(float lo, float hi) { unsigned r; asm volatile("v_cvt_pk_bf16_f32 %0, %1, %2" : "=v"(r) : "v"(lo), "v"(hi)); return r; }
; DI float bflo(unsigned w) { return __uint_as_float(w << 16); }
; DI float bfhi(unsigned w) { return __uint_as_float(w & 0xffff0000u); }
; DI float sigm(float x) { return rcpf_(1.f + ex2(-x * LOG2E)); }
; DI void attn_item(const bf16_t* __restrict__ Qw_, const bf16_t* __restrict__ Kh, const bf16_t* __restrict__ Vh, const bf16_t* Gw, bf16_t* Ow,
;                   int NT, int kt0, int qw, float sinkv, char* lds) {
;     ...
; #pragma unroll
;     for (int k = 0; k < 8; ++k) {
;         const u32x4 ov = *(const u32x4*)(OT + (er + 4 * k) * 136 + ec * 8); u32x4 w;
; #pragma unroll
;         for (int i = 0; i < 4; ++i) { const float g0 = bflo(gv[k][i]), g1 = bfhi(gv[k][i]); w[i] = cvtpk(bflo(ov[i]) * g0 * sigm(g0), bfhi(ov[i]) * g1 * sigm(g1)); }
;         __builtin_nontemporal_store(w, (u32x4*)(Ow + (size_t)(er + 4 * k) * 2048 + ec * 8));
;     }
	v_lshlrev_b32_e32 v39, 16, v46
	v_rcp_f32_e32 v40, v40
	v_mul_f32_e32 v38, v39, v38
	v_add_f32_e32 v39, 1.0, v42
	v_rcp_f32_e32 v39, v39
	v_mul_f32_e32 v38, v40, v38
	v_and_b32_e32 v40, 0xffff0000, v46
	v_mul_f32_e32 v40, v40, v41
	v_mul_f32_e32 v39, v39, v40
	v_cvt_pk_bf16_f32 v38, v38, v39
	v_lshlrev_b32_e32 v39, 16, v43
	v_mul_f32_e32 v41, 0xbfb8aa3b, v39
	v_exp_f32_e32 v41, v41
	v_and_b32_e32 v42, 0xffff0000, v43
	v_mul_f32_e32 v43, 0xbfb8aa3b, v42
	v_exp_f32_e32 v43, v43
	v_add_f32_e32 v41, 1.0, v41
	v_lshlrev_b32_e32 v40, 16, v47
	v_rcp_f32_e32 v41, v41
	v_mul_f32_e32 v39, v40, v39
	v_add_f32_e32 v40, 1.0, v43
	v_rcp_f32_e32 v40, v40
	v_mul_f32_e32 v39, v41, v39
	v_and_b32_e32 v41, 0xffff0000, v47
	v_mul_f32_e32 v41, v41, v42
	v_mul_f32_e32 v40, v40, v41
	v_cvt_pk_bf16_f32 v39, v39, v40
	v_lshlrev_b32_e32 v40, 16, v44
	v_mul_f32_e32 v42, 0xbfb8aa3b, v40
	v_exp_f32_e32 v42, v42
	v_and_b32_e32 v43, 0xffff0000, v44
	v_mul_f32_e32 v44, 0xbfb8aa3b, v43
	v_exp_f32_e32 v44, v44
	v_add_f32_e32 v42, 1.0, v42
	v_lshlrev_b32_e32 v41, 16, v48
	v_rcp_f32_e32 v42, v42
	v_mul_f32_e32 v40, v41, v40
	v_add_f32_e32 v41, 1.0, v44
	v_rcp_f32_e32 v41, v41
	v_mul_f32_e32 v40, v42, v40
	v_and_b32_e32 v42, 0xffff0000, v48
	v_mul_f32_e32 v42, v42, v43
	v_mul_f32_e32 v41, v41, v42
	v_cvt_pk_bf16_f32 v40, v40, v41
	v_lshlrev_b32_e32 v41, 16, v45
	v_mul_f32_e32 v43, 0xbfb8aa3b, v41
	v_exp_f32_e32 v43, v43
	v_and_b32_e32 v44, 0xffff0000, v45
	v_mul_f32_e32 v45, 0xbfb8aa3b, v44
	v_exp_f32_e32 v45, v45
	v_add_f32_e32 v43, 1.0, v43
	v_lshlrev_b32_e32 v42, 16, v49
	v_rcp_f32_e32 v43, v43
	v_mul_f32_e32 v41, v42, v41
	v_add_f32_e32 v42, 1.0, v45
	v_rcp_f32_e32 v42, v42
	v_mul_f32_e32 v41, v43, v41
	v_and_b32_e32 v43, 0xffff0000, v49
	v_mul_f32_e32 v43, v43, v44
	v_mul_f32_e32 v42, v42, v43
	v_cvt_pk_bf16_f32 v41, v41, v42
	global_store_dwordx4 v[52:53], v[38:41], off nt
	ds_read_b128 v[42:45], v0 offset:2176
	s_waitcnt vmcnt(7)
	v_lshlrev_b32_e32 v38, 16, v22
	v_mul_f32_e32 v40, 0xbfb8aa3b, v38
	v_exp_f32_e32 v40, v40
	v_and_b32_e32 v22, 0xffff0000, v22
	v_mul_f32_e32 v41, 0xbfb8aa3b, v22
	v_exp_f32_e32 v41, v41
	v_add_f32_e32 v40, 1.0, v40
	s_waitcnt lgkmcnt(0)
	v_lshlrev_b32_e32 v39, 16, v42
	v_rcp_f32_e32 v40, v40
	v_mul_f32_e32 v38, v39, v38
	v_add_f32_e32 v39, 1.0, v41
	v_rcp_f32_e32 v39, v39
	v_mul_f32_e32 v38, v40, v38
	v_and_b32_e32 v40, 0xffff0000, v42
	v_mul_f32_e32 v22, v40, v22
	v_mul_f32_e32 v22, v39, v22
	v_cvt_pk_bf16_f32 v22, v38, v22
	v_lshlrev_b32_e32 v38, 16, v23
	v_mul_f32_e32 v40, 0xbfb8aa3b, v38
	v_exp_f32_e32 v40, v40
	v_and_b32_e32 v23, 0xffff0000, v23
	v_mul_f32_e32 v41, 0xbfb8aa3b, v23
	v_exp_f32_e32 v41, v41
	v_add_f32_e32 v40, 1.0, v40
	v_lshlrev_b32_e32 v39, 16, v43
	v_rcp_f32_e32 v40, v40
	v_mul_f32_e32 v38, v39, v38
	v_add_f32_e32 v39, 1.0, v41
	v_rcp_f32_e32 v39, v39
	v_mul_f32_e32 v38, v40, v38
	v_and_b32_e32 v40, 0xffff0000, v43
	v_mul_f32_e32 v23, v40, v23
	v_mul_f32_e32 v23, v39, v23
	v_cvt_pk_bf16_f32 v23, v38, v23
	v_lshlrev_b32_e32 v38, 16, v24
	v_mul_f32_e32 v40, 0xbfb8aa3b, v38
	v_exp_f32_e32 v40, v40
	v_and_b32_e32 v24, 0xffff0000, v24
	v_mul_f32_e32 v41, 0xbfb8aa3b, v24
	v_exp_f32_e32 v41, v41
	v_add_f32_e32 v40, 1.0, v40
	v_lshlrev_b32_e32 v39, 16, v44
	v_rcp_f32_e32 v40, v40
	v_mul_f32_e32 v38, v39, v38
	v_add_f32_e32 v39, 1.0, v41
	v_rcp_f32_e32 v39, v39
	v_mul_f32_e32 v38, v40, v38
	v_and_b32_e32 v40, 0xffff0000, v44
	v_mul_f32_e32 v24, v40, v24
	v_mul_f32_e32 v24, v39, v24
	v_cvt_pk_bf16_f32 v24, v38, v24
	v_lshlrev_b32_e32 v38, 16, v25
	v_mul_f32_e32 v40, 0xbfb8aa3b, v38
	v_exp_f32_e32 v40, v40
	v_and_b32_e32 v25, 0xffff0000, v25
	v_mul_f32_e32 v41, 0xbfb8aa3b, v25
	v_exp_f32_e32 v41, v41
	v_add_f32_e32 v40, 1.0, v40
	v_lshlrev_b32_e32 v39, 16, v45
	v_rcp_f32_e32 v40, v40
	v_mul_f32_e32 v38, v39, v38
	v_add_f32_e32 v39, 1.0, v41
	v_rcp_f32_e32 v39, v39
	v_mul_f32_e32 v38, v40, v38
	v_and_b32_e32 v40, 0xffff0000, v45
	v_mul_f32_e32 v25, v40, v25
	v_mul_f32_e32 v25, v39, v25
	v_cvt_pk_bf16_f32 v25, v38, v25
	global_store_dwordx4 v[36:37], v[22:25], off nt
	ds_read_b128 v[38:41], v0 offset:3264
	s_waitcnt vmcnt(7)
	v_lshlrev_b32_e32 v22, 16, v18
	v_mul_f32_e32 v24, 0xbfb8aa3b, v22
	v_exp_f32_e32 v24, v24
	v_and_b32_e32 v18, 0xffff0000, v18
	v_mul_f32_e32 v25, 0xbfb8aa3b, v18
	v_exp_f32_e32 v25, v25
	v_add_f32_e32 v24, 1.0, v24
	s_waitcnt lgkmcnt(0)
	v_lshlrev_b32_e32 v23, 16, v38
	v_rcp_f32_e32 v24, v24
	v_mul_f32_e32 v22, v23, v22
	v_add_f32_e32 v23, 1.0, v25
	v_rcp_f32_e32 v23, v23
	v_mul_f32_e32 v22, v24, v22
	v_and_b32_e32 v24, 0xffff0000, v38
	v_mul_f32_e32 v18, v24, v18
	v_mul_f32_e32 v18, v23, v18
	v_cvt_pk_bf16_f32 v18, v22, v18
	v_lshlrev_b32_e32 v22, 16, v19
	v_mul_f32_e32 v24, 0xbfb8aa3b, v22
	v_exp_f32_e32 v24, v24
	v_and_b32_e32 v19, 0xffff0000, v19
	v_mul_f32_e32 v25, 0xbfb8aa3b, v19
	v_exp_f32_e32 v25, v25
	v_add_f32_e32 v24, 1.0, v24
	v_lshlrev_b32_e32 v23, 16, v39
	v_rcp_f32_e32 v24, v24
	v_mul_f32_e32 v22, v23, v22
	v_add_f32_e32 v23, 1.0, v25
	v_rcp_f32_e32 v23, v23
	v_mul_f32_e32 v22, v24, v22
	v_and_b32_e32 v24, 0xffff0000, v39
	v_mul_f32_e32 v19, v24, v19
	v_mul_f32_e32 v19, v23, v19
	v_cvt_pk_bf16_f32 v19, v22, v19
	v_lshlrev_b32_e32 v22, 16, v20
	v_mul_f32_e32 v24, 0xbfb8aa3b, v22
	v_exp_f32_e32 v24, v24
	v_and_b32_e32 v20, 0xffff0000, v20
	v_mul_f32_e32 v25, 0xbfb8aa3b, v20
	v_exp_f32_e32 v25, v25
	v_add_f32_e32 v24, 1.0, v24
	v_lshlrev_b32_e32 v23, 16, v40
	v_rcp_f32_e32 v24, v24
	v_mul_f32_e32 v22, v23, v22
	v_add_f32_e32 v23, 1.0, v25
	v_rcp_f32_e32 v23, v23
	v_mul_f32_e32 v22, v24, v22
	v_and_b32_e32 v24, 0xffff0000, v40
	v_mul_f32_e32 v20, v24, v20
	v_mul_f32_e32 v20, v23, v20
	v_cvt_pk_bf16_f32 v20, v22, v20
	v_lshlrev_b32_e32 v22, 16, v21
	v_mul_f32_e32 v24, 0xbfb8aa3b, v22
	v_exp_f32_e32 v24, v24
	v_and_b32_e32 v21, 0xffff0000, v21
	v_mul_f32_e32 v25, 0xbfb8aa3b, v21
	v_exp_f32_e32 v25, v25
	v_add_f32_e32 v24, 1.0, v24
	v_lshlrev_b32_e32 v23, 16, v41
	v_rcp_f32_e32 v24, v24
	v_mul_f32_e32 v22, v23, v22
	v_add_f32_e32 v23, 1.0, v25
	v_rcp_f32_e32 v23, v23
	v_mul_f32_e32 v22, v24, v22
	v_and_b32_e32 v24, 0xffff0000, v41
	v_mul_f32_e32 v21, v24, v21
	v_mul_f32_e32 v21, v23, v21
	v_cvt_pk_bf16_f32 v21, v22, v21
	global_store_dwordx4 v[34:35], v[18:21], off nt
	ds_read_b128 v[22:25], v0 offset:4352
	s_waitcnt vmcnt(7)
; DI unsigned cvtpk(float lo, float hi) { unsigned r; asm volatile("v_cvt_pk_bf16_f32 %0, %1, %2" : "=v"(r) : "v"(lo), "v"(hi)); return r; }
; DI float bflo(unsigned w) { return __uint_as_float(w << 16); }
; DI float bfhi(unsigned w) { return __uint_as_float(w & 0xffff0000u); }
; DI float sigm(float x) { return rcpf_(1.f + ex2(-x * LOG2E)); }
; DI void attn_item(const bf16_t* __restrict__ Qw_, const bf16_t* __restrict__ Kh, const bf16_t* __restrict__ Vh, const bf16_t* Gw, bf16_t* Ow,
;                   int NT, int kt0, int qw, float sinkv, char* lds) {
;     ...
; #pragma unroll
;     for (int k = 0; k < 8; ++k) {
;         const u32x4 ov = *(const u32x4*)(OT + (er + 4 * k) * 136 + ec * 8); u32x4 w;
; #pragma unroll
;         for (int i = 0; i < 4; ++i) { const float g0 = bflo(gv[k][i]), g1 = bfhi(gv[k][i]); w[i] = cvtpk(bflo(ov[i]) * g0 * sigm(g0), bfhi(ov[i]) * g1 * sigm(g1)); }
;         __builtin_nontemporal_store(w, (u32x4*)(Ow + (size_t)(er + 4 * k) * 2048 + ec * 8));
;     }
	v_lshlrev_b32_e32 v18, 16, v14
	v_mul_f32_e32 v20, 0xbfb8aa3b, v18
	v_exp_f32_e32 v20, v20
	v_and_b32_e32 v14, 0xffff0000, v14
	v_mul_f32_e32 v21, 0xbfb8aa3b, v14
	v_exp_f32_e32 v21, v21
	v_add_f32_e32 v20, 1.0, v20
	s_waitcnt lgkmcnt(0)
	v_lshlrev_b32_e32 v19, 16, v22
	v_rcp_f32_e32 v20, v20
	v_mul_f32_e32 v18, v19, v18
	v_add_f32_e32 v19, 1.0, v21
	v_rcp_f32_e32 v19, v19
	v_mul_f32_e32 v18, v20, v18
	v_and_b32_e32 v20, 0xffff0000, v22
	v_mul_f32_e32 v14, v20, v14
	v_mul_f32_e32 v14, v19, v14
	v_cvt_pk_bf16_f32 v14, v18, v14
	v_lshlrev_b32_e32 v18, 16, v15
	v_mul_f32_e32 v20, 0xbfb8aa3b, v18
	v_exp_f32_e32 v20, v20
	v_and_b32_e32 v15, 0xffff0000, v15
	v_mul_f32_e32 v21, 0xbfb8aa3b, v15
	v_exp_f32_e32 v21, v21
	v_add_f32_e32 v20, 1.0, v20
	v_lshlrev_b32_e32 v19, 16, v23
	v_rcp_f32_e32 v20, v20
	v_mul_f32_e32 v18, v19, v18
	v_add_f32_e32 v19, 1.0, v21
	v_rcp_f32_e32 v19, v19
	v_mul_f32_e32 v18, v20, v18
	v_and_b32_e32 v20, 0xffff0000, v23
	v_mul_f32_e32 v15, v20, v15
	v_mul_f32_e32 v15, v19, v15
	v_cvt_pk_bf16_f32 v15, v18, v15
	v_lshlrev_b32_e32 v18, 16, v16
	v_mul_f32_e32 v20, 0xbfb8aa3b, v18
	v_exp_f32_e32 v20, v20
	v_and_b32_e32 v16, 0xffff0000, v16
	v_mul_f32_e32 v21, 0xbfb8aa3b, v16
	v_exp_f32_e32 v21, v21
	v_add_f32_e32 v20, 1.0, v20
	v_lshlrev_b32_e32 v19, 16, v24
	v_rcp_f32_e32 v20, v20
	v_mul_f32_e32 v18, v19, v18
	v_add_f32_e32 v19, 1.0, v21
	v_rcp_f32_e32 v19, v19
	v_mul_f32_e32 v18, v20, v18
	v_and_b32_e32 v20, 0xffff0000, v24
	v_mul_f32_e32 v16, v20, v16
	v_mul_f32_e32 v16, v19, v16
	v_cvt_pk_bf16_f32 v16, v18, v16
	v_lshlrev_b32_e32 v18, 16, v17
	v_mul_f32_e32 v20, 0xbfb8aa3b, v18
	v_exp_f32_e32 v20, v20
	v_and_b32_e32 v17, 0xffff0000, v17
	v_mul_f32_e32 v21, 0xbfb8aa3b, v17
	v_exp_f32_e32 v21, v21
	v_add_f32_e32 v20, 1.0, v20
	v_lshlrev_b32_e32 v19, 16, v25
	v_rcp_f32_e32 v20, v20
	v_mul_f32_e32 v18, v19, v18
	v_add_f32_e32 v19, 1.0, v21
	v_rcp_f32_e32 v19, v19
	v_mul_f32_e32 v18, v20, v18
	v_and_b32_e32 v20, 0xffff0000, v25
	v_mul_f32_e32 v17, v20, v17
	v_mul_f32_e32 v17, v19, v17
	v_cvt_pk_bf16_f32 v17, v18, v17
	global_store_dwordx4 v[32:33], v[14:17], off nt
	ds_read_b128 v[18:21], v0 offset:5440
	s_waitcnt vmcnt(7)
	v_lshlrev_b32_e32 v14, 16, v10
	v_mul_f32_e32 v16, 0xbfb8aa3b, v14
	v_exp_f32_e32 v16, v16
	v_and_b32_e32 v10, 0xffff0000, v10
	v_mul_f32_e32 v17, 0xbfb8aa3b, v10
	v_exp_f32_e32 v17, v17
	v_add_f32_e32 v16, 1.0, v16
	s_waitcnt lgkmcnt(0)
	v_lshlrev_b32_e32 v15, 16, v18
	v_rcp_f32_e32 v16, v16
	v_mul_f32_e32 v14, v15, v14
	v_add_f32_e32 v15, 1.0, v17
	v_rcp_f32_e32 v15, v15
	v_mul_f32_e32 v14, v16, v14
	v_and_b32_e32 v16, 0xffff0000, v18
	v_mul_f32_e32 v10, v16, v10
	v_mul_f32_e32 v10, v15, v10
	v_cvt_pk_bf16_f32 v10, v14, v10
	v_lshlrev_b32_e32 v14, 16, v11
	v_mul_f32_e32 v16, 0xbfb8aa3b, v14
	v_exp_f32_e32 v16, v16
	v_and_b32_e32 v11, 0xffff0000, v11
	v_mul_f32_e32 v17, 0xbfb8aa3b, v11
	v_exp_f32_e32 v17, v17
	v_add_f32_e32 v16, 1.0, v16
	v_lshlrev_b32_e32 v15, 16, v19
	v_rcp_f32_e32 v16, v16
	v_mul_f32_e32 v14, v15, v14
	v_add_f32_e32 v15, 1.0, v17
	v_rcp_f32_e32 v15, v15
	v_mul_f32_e32 v14, v16, v14
	v_and_b32_e32 v16, 0xffff0000, v19
	v_mul_f32_e32 v11, v16, v11
	v_mul_f32_e32 v11, v15, v11
	v_cvt_pk_bf16_f32 v11, v14, v11
	v_lshlrev_b32_e32 v14, 16, v12
	v_mul_f32_e32 v16, 0xbfb8aa3b, v14
	v_exp_f32_e32 v16, v16
	v_and_b32_e32 v12, 0xffff0000, v12
	v_mul_f32_e32 v17, 0xbfb8aa3b, v12
	v_exp_f32_e32 v17, v17
	v_add_f32_e32 v16, 1.0, v16
	v_lshlrev_b32_e32 v15, 16, v20
	v_rcp_f32_e32 v16, v16
	v_mul_f32_e32 v14, v15, v14
	v_add_f32_e32 v15, 1.0, v17
	v_rcp_f32_e32 v15, v15
	v_mul_f32_e32 v14, v16, v14
	v_and_b32_e32 v16, 0xffff0000, v20
	v_mul_f32_e32 v12, v16, v12
	v_mul_f32_e32 v12, v15, v12
	v_cvt_pk_bf16_f32 v12, v14, v12
	v_lshlrev_b32_e32 v14, 16, v13
	v_mul_f32_e32 v16, 0xbfb8aa3b, v14
	v_exp_f32_e32 v16, v16
	v_and_b32_e32 v13, 0xffff0000, v13
	v_mul_f32_e32 v17, 0xbfb8aa3b, v13
	v_exp_f32_e32 v17, v17
	v_add_f32_e32 v16, 1.0, v16
	v_lshlrev_b32_e32 v15, 16, v21
	v_rcp_f32_e32 v16, v16
	v_mul_f32_e32 v14, v15, v14
	v_add_f32_e32 v15, 1.0, v17
	v_rcp_f32_e32 v15, v15
	v_mul_f32_e32 v14, v16, v14
	v_and_b32_e32 v16, 0xffff0000, v21
	v_mul_f32_e32 v13, v16, v13
	v_mul_f32_e32 v13, v15, v13
	v_cvt_pk_bf16_f32 v13, v14, v13
	global_store_dwordx4 v[30:31], v[10:13], off nt
	ds_read_b128 v[14:17], v0 offset:6528
	s_waitcnt vmcnt(7)
; DI unsigned cvtpk(float lo, float hi) { unsigned r; asm volatile("v_cvt_pk_bf16_f32 %0, %1, %2" : "=v"(r) : "v"(lo), "v"(hi)); return r; }
; DI float bflo(unsigned w) { return __uint_as_float(w << 16); }
; DI float bfhi(unsigned w) { return __uint_as_float(w & 0xffff0000u); }
; DI float sigm(float x) { return rcpf_(1.f + ex2(-x * LOG2E)); }
; DI void attn_item(const bf16_t* __restrict__ Qw_, const bf16_t* __restrict__ Kh, const bf16_t* __restrict__ Vh, const bf16_t* Gw, bf16_t* Ow,
;                   int NT, int kt0, int qw, float sinkv, char* lds) {
;     ...
; #pragma unroll
;     for (int k = 0; k < 8; ++k) {
;         const u32x4 ov = *(const u32x4*)(OT + (er + 4 * k) * 136 + ec * 8); u32x4 w;
; #pragma unroll
;         for (int i = 0; i < 4; ++i) { const float g0 = bflo(gv[k][i]), g1 = bfhi(gv[k][i]); w[i] = cvtpk(bflo(ov[i]) * g0 * sigm(g0), bfhi(ov[i]) * g1 * sigm(g1)); }
;         __builtin_nontemporal_store(w, (u32x4*)(Ow + (size_t)(er + 4 * k) * 2048 + ec * 8));
;     }
	v_lshlrev_b32_e32 v10, 16, v6
	v_mul_f32_e32 v12, 0xbfb8aa3b, v10
	v_exp_f32_e32 v12, v12
	v_and_b32_e32 v6, 0xffff0000, v6
	v_mul_f32_e32 v13, 0xbfb8aa3b, v6
	v_exp_f32_e32 v13, v13
	v_add_f32_e32 v12, 1.0, v12
	s_waitcnt lgkmcnt(0)
	v_lshlrev_b32_e32 v11, 16, v14
	v_rcp_f32_e32 v12, v12
	v_mul_f32_e32 v10, v11, v10
	v_add_f32_e32 v11, 1.0, v13
	v_rcp_f32_e32 v11, v11
	v_mul_f32_e32 v10, v12, v10
	v_and_b32_e32 v12, 0xffff0000, v14
	v_mul_f32_e32 v6, v12, v6
	v_mul_f32_e32 v6, v11, v6
	v_cvt_pk_bf16_f32 v6, v10, v6
	v_lshlrev_b32_e32 v10, 16, v7
	v_mul_f32_e32 v12, 0xbfb8aa3b, v10
	v_exp_f32_e32 v12, v12
	v_and_b32_e32 v7, 0xffff0000, v7
	v_mul_f32_e32 v13, 0xbfb8aa3b, v7
	v_exp_f32_e32 v13, v13
	v_add_f32_e32 v12, 1.0, v12
	v_lshlrev_b32_e32 v11, 16, v15
	v_rcp_f32_e32 v12, v12
	v_mul_f32_e32 v10, v11, v10
	v_add_f32_e32 v11, 1.0, v13
	v_rcp_f32_e32 v11, v11
	v_mul_f32_e32 v10, v12, v10
	v_and_b32_e32 v12, 0xffff0000, v15
	v_mul_f32_e32 v7, v12, v7
	v_mul_f32_e32 v7, v11, v7
	v_cvt_pk_bf16_f32 v7, v10, v7
	v_lshlrev_b32_e32 v10, 16, v8
	v_mul_f32_e32 v12, 0xbfb8aa3b, v10
	v_exp_f32_e32 v12, v12
	v_and_b32_e32 v8, 0xffff0000, v8
	v_mul_f32_e32 v13, 0xbfb8aa3b, v8
	v_exp_f32_e32 v13, v13
	v_add_f32_e32 v12, 1.0, v12
	v_lshlrev_b32_e32 v11, 16, v16
	v_rcp_f32_e32 v12, v12
	v_mul_f32_e32 v10, v11, v10
	v_add_f32_e32 v11, 1.0, v13
	v_rcp_f32_e32 v11, v11
	v_mul_f32_e32 v10, v12, v10
	v_and_b32_e32 v12, 0xffff0000, v16
	v_mul_f32_e32 v8, v12, v8
	v_mul_f32_e32 v8, v11, v8
	v_cvt_pk_bf16_f32 v8, v10, v8
	v_lshlrev_b32_e32 v10, 16, v9
	v_mul_f32_e32 v12, 0xbfb8aa3b, v10
	v_exp_f32_e32 v12, v12
	v_and_b32_e32 v9, 0xffff0000, v9
	v_mul_f32_e32 v13, 0xbfb8aa3b, v9
	v_exp_f32_e32 v13, v13
	v_add_f32_e32 v12, 1.0, v12
	v_lshlrev_b32_e32 v11, 16, v17
	v_rcp_f32_e32 v12, v12
	v_mul_f32_e32 v10, v11, v10
	v_add_f32_e32 v11, 1.0, v13
	v_rcp_f32_e32 v11, v11
	v_mul_f32_e32 v10, v12, v10
	v_and_b32_e32 v12, 0xffff0000, v17
	v_mul_f32_e32 v9, v12, v9
	v_mul_f32_e32 v9, v11, v9
	v_cvt_pk_bf16_f32 v9, v10, v9
	ds_read_b128 v[10:13], v0 offset:7616
	s_waitcnt vmcnt(6)
	v_lshlrev_b32_e32 v0, 16, v2
	global_store_dwordx4 v[28:29], v[6:9], off nt
	v_and_b32_e32 v2, 0xffff0000, v2
	s_nop 0
	v_mul_f32_e32 v7, 0xbfb8aa3b, v0
	v_exp_f32_e32 v7, v7
	v_mul_f32_e32 v8, 0xbfb8aa3b, v2
	v_exp_f32_e32 v8, v8
	s_waitcnt lgkmcnt(0)
	v_lshlrev_b32_e32 v6, 16, v10
	v_add_f32_e32 v7, 1.0, v7
	v_rcp_f32_e32 v7, v7
	v_mul_f32_e32 v0, v6, v0
	v_add_f32_e32 v6, 1.0, v8
	v_rcp_f32_e32 v6, v6
	v_mul_f32_e32 v0, v7, v0
	v_and_b32_e32 v7, 0xffff0000, v10
	v_mul_f32_e32 v2, v7, v2
	v_mul_f32_e32 v2, v6, v2
	v_cvt_pk_bf16_f32 v2, v0, v2
	v_lshlrev_b32_e32 v0, 16, v3
	v_mul_f32_e32 v7, 0xbfb8aa3b, v0
	v_exp_f32_e32 v7, v7
	v_and_b32_e32 v3, 0xffff0000, v3
	v_mul_f32_e32 v8, 0xbfb8aa3b, v3
	v_exp_f32_e32 v8, v8
	v_add_f32_e32 v7, 1.0, v7
	v_lshlrev_b32_e32 v6, 16, v11
	v_rcp_f32_e32 v7, v7
	v_mul_f32_e32 v0, v6, v0
	v_add_f32_e32 v6, 1.0, v8
	v_rcp_f32_e32 v6, v6
	v_mul_f32_e32 v0, v7, v0
	v_and_b32_e32 v7, 0xffff0000, v11
	v_mul_f32_e32 v3, v7, v3
	v_mul_f32_e32 v3, v6, v3
	v_cvt_pk_bf16_f32 v3, v0, v3
	v_lshlrev_b32_e32 v0, 16, v4
	v_mul_f32_e32 v7, 0xbfb8aa3b, v0
	v_exp_f32_e32 v7, v7
	v_and_b32_e32 v4, 0xffff0000, v4
	v_mul_f32_e32 v8, 0xbfb8aa3b, v4
	v_exp_f32_e32 v8, v8
	v_add_f32_e32 v7, 1.0, v7
	v_lshlrev_b32_e32 v6, 16, v12
	v_rcp_f32_e32 v7, v7
	v_mul_f32_e32 v0, v6, v0
	v_add_f32_e32 v6, 1.0, v8
	v_rcp_f32_e32 v6, v6
	v_mul_f32_e32 v0, v7, v0
	v_and_b32_e32 v7, 0xffff0000, v12
	v_mul_f32_e32 v4, v7, v4
	v_mul_f32_e32 v4, v6, v4
	v_cvt_pk_bf16_f32 v4, v0, v4
	v_lshlrev_b32_e32 v0, 16, v5
	v_mul_f32_e32 v7, 0xbfb8aa3b, v0
	v_exp_f32_e32 v7, v7
	v_and_b32_e32 v5, 0xffff0000, v5
	v_mul_f32_e32 v8, 0xbfb8aa3b, v5
	v_exp_f32_e32 v8, v8
	v_add_f32_e32 v7, 1.0, v7
	v_lshlrev_b32_e32 v6, 16, v13
	v_rcp_f32_e32 v7, v7
	v_mul_f32_e32 v0, v6, v0
	v_add_f32_e32 v6, 1.0, v8
	v_rcp_f32_e32 v6, v6
	v_mul_f32_e32 v0, v7, v0
	v_and_b32_e32 v7, 0xffff0000, v13
	v_mul_f32_e32 v5, v7, v5
	v_mul_f32_e32 v5, v6, v5
	v_cvt_pk_bf16_f32 v5, v0, v5
	global_store_dwordx4 v[26:27], v[2:5], off nt
	s_cbranch_scc0 .LBB0_265
